# outproj epilogue: X stores as full 128B lines via dpp row_ror:8 lane exchange
# speedup vs baseline: 1.0024x; 1.0024x over previous
; __device__ __forceinline__ unsigned cvt_pk_bf16(float lo, float hi) { unsigned r; asm volatile("v_cvt_pk_bf16_f32 %0, %1, %2" : "=v"(r) : "v"(lo), "v"(hi)); return r; }
;     __device__ __forceinline__ void operator()(const f32x4 (&acc)[2][2][4][2], const Unit& u, int wr, int wc, int fr, int fq) const {
;         const int row0 = u.pm * BM + wr * 64 + fr, col0 = u.pn * BM + wc * 32 + 8 * fq;
;         f32x4 gv[2][2];
; #pragma unroll
;         for (int bj = 0; bj < 2; ++bj)
; #pragma unroll
;             for (int n = 0; n < 2; ++n) gv[bj][n] = *(const f32x4*)(g + col0 + bj * HALF + 4 * n);
; #pragma unroll
;         for (int ai = 0; ai < 2; ++ai) {
;             f32x4 rb[4][2][2];
; #pragma unroll
;             for (int m = 0; m < 4; ++m) { const size_t off = (size_t)(row0 + ai * HALF + m * 16) * ldc + col0;
; #pragma unroll
;                 for (int bj = 0; bj < 2; ++bj) { rb[m][bj][0] = *(const f32x4*)(base + off + bj * HALF); rb[m][bj][1] = *(const f32x4*)(base + off + bj * HALF + 4); } }
; #pragma unroll
;             for (int m = 0; m < 4; ++m) { const int row = row0 + ai * HALF + m * 16; const size_t off = (size_t)row * ldc + col0; float ss = 0.f;
; #pragma unroll
;                 for (int bj = 0; bj < 2; ++bj) {
;                     const f32x4 x0 = rb[m][bj][0] + acc[ai][bj][m][0], x1 = rb[m][bj][1] + acc[ai][bj][m][1];
;                     if (out) { *(f32x4*)(out + off + bj * HALF) = x0; *(f32x4*)(out + off + bj * HALF + 4) = x1; }
;                     ss += (x0[0] * x0[0] + x0[1] * x0[1]) + (x0[2] * x0[2] + x0[3] * x0[3]) + (x1[0] * x1[0] + x1[1] * x1[1]) + (x1[2] * x1[2] + x1[3] * x1[3]);
;                     const f32x4 y0 = x0 * gv[bj][0], y1 = x1 * gv[bj][1];
;                     u32x4 w; w.x = cvt_pk_bf16(y0[0], y0[1]); w.y = cvt_pk_bf16(y0[2], y0[3]); w.z = cvt_pk_bf16(y1[0], y1[1]); w.w = cvt_pk_bf16(y1[2], y1[3]);
;                     *(u32x4*)(XG + off + bj * HALF) = w; }
;                 ss += __shfl_xor(ss, 16); ss += __shfl_xor(ss, 32);
;                 if (fq == 0) SS[(size_t)row * 32 + u.pn * 4 + wc] = ss; }
.LBB0_1784:
	v_lshl_or_b32 v218, s40, 8, v232
	v_ashrrev_i32_e32 v219, 31, v218
	v_lshl_add_u32 v222, s34, 8, v230
	v_ashrrev_i32_e32 v223, 31, v222
	v_lshlrev_b64 v[220:221], 2, v[218:219]
	v_lshl_add_u64 v[224:225], s[14:15], 0, v[220:221]
	global_load_dwordx4 v[56:59], v[224:225], off
	global_load_dwordx4 v[60:63], v[224:225], off offset:16
	global_load_dwordx4 v[64:67], v[224:225], off offset:512
	global_load_dwordx4 v[68:71], v[224:225], off offset:528
	v_lshl_add_u64 v[220:221], s[10:11], 0, v[220:221]
	v_lshlrev_b64 v[234:235], 13, v[222:223]
	v_lshl_add_u64 v[220:221], v[220:221], 0, v[234:235]
	s_mov_b32 s35, 0
	s_mov_b32 s34, 0x0
	v_lshl_add_u64 v[224:225], v[220:221], 0, s[34:35]
	global_load_dwordx4 v[146:149], v[224:225], off
	global_load_dwordx4 v[150:153], v[224:225], off offset:16
	global_load_dwordx4 v[154:157], v[224:225], off offset:512
	global_load_dwordx4 v[158:161], v[224:225], off offset:528
	s_mov_b32 s34, 0x20000
	v_lshl_add_u64 v[224:225], v[220:221], 0, s[34:35]
	global_load_dwordx4 v[162:165], v[224:225], off
	global_load_dwordx4 v[166:169], v[224:225], off offset:16
	global_load_dwordx4 v[170:173], v[224:225], off offset:512
	global_load_dwordx4 v[174:177], v[224:225], off offset:528
	s_mov_b32 s34, 0x40000
	v_lshl_add_u64 v[224:225], v[220:221], 0, s[34:35]
	global_load_dwordx4 v[178:181], v[224:225], off
	global_load_dwordx4 v[182:185], v[224:225], off offset:16
	global_load_dwordx4 v[186:189], v[224:225], off offset:512
	global_load_dwordx4 v[190:193], v[224:225], off offset:528
	v_lshlrev_b64 v[226:227], 7, v[222:223]
	v_lshl_add_u64 v[226:227], s[18:19], 0, v[226:227]
	s_lshl_b32 s46, s61, 2
	s_lshl_b32 s34, s40, 4
	s_add_i32 s46, s46, s34
	v_lshl_add_u64 v[226:227], v[226:227], 0, s[46:47]
	v_lshlrev_b64 v[228:229], 12, v[222:223]
	v_lshl_add_u64 v[228:229], s[16:17], 0, v[228:229]
	v_lshlrev_b64 v[234:235], 1, v[218:219]
	v_lshl_add_u64 v[228:229], v[228:229], 0, v[234:235]
	s_sub_u32 s40, s8, s10
	s_subb_u32 s41, s9, s11
	v_xor_b32_e32 v194, 16, v254
	v_xor_b32_e32 v195, 32, v254
	v_lshlrev_b32_e32 v194, 2, v194
	v_lshlrev_b32_e32 v195, 2, v195
	v_and_b32_e32 v196, 15, v254
	v_cmp_gt_u32_e32 vcc, 8, v196
	v_mov_b32_e32 v197, 0
	v_mov_b32_e32 v198, 16
	v_mov_b32_e32 v199, 0x10000
	v_mov_b32_e32 v196, 0xffff0010
	v_cndmask_b32_e32 v218, v196, v197, vcc
	v_cndmask_b32_e32 v222, v198, v199, vcc
	v_ashrrev_i32_e32 v219, 31, v218
	v_mov_b32_e32 v223, 0
	s_waitcnt vmcnt(8)
	v_pk_add_f32 v[142:143], v[142:143], v[146:147]
	v_pk_add_f32 v[144:145], v[144:145], v[148:149]
	v_pk_add_f32 v[138:139], v[138:139], v[150:151]
	v_pk_add_f32 v[140:141], v[140:141], v[152:153]
	v_pk_add_f32 v[134:135], v[134:135], v[154:155]
	v_pk_add_f32 v[136:137], v[136:137], v[156:157]
	v_pk_add_f32 v[130:131], v[130:131], v[158:159]
	v_pk_add_f32 v[132:133], v[132:133], v[160:161]
	s_mov_b32 s34, 0x60000
	v_lshl_add_u64 v[224:225], v[220:221], 0, s[34:35]
	global_load_dwordx4 v[146:149], v[224:225], off
	global_load_dwordx4 v[150:153], v[224:225], off offset:16
	global_load_dwordx4 v[154:157], v[224:225], off offset:512
	global_load_dwordx4 v[158:161], v[224:225], off offset:528
	s_mov_b32 s34, 0x0
	v_lshl_add_u64 v[224:225], v[220:221], 0, s[34:35]
	v_lshl_add_u64 v[224:225], v[224:225], 0, s[40:41]
	v_lshl_add_u64 v[234:235], v[224:225], 0, v[222:223]
	v_lshl_add_u64 v[224:225], v[224:225], 0, v[218:219]
	v_cndmask_b32_dpp v200, v138, v142, vcc row_ror:8 row_mask:0xf bank_mask:0xf
	v_cndmask_b32_dpp v201, v139, v143, vcc row_ror:8 row_mask:0xf bank_mask:0xf
	v_cndmask_b32_dpp v202, v140, v144, vcc row_ror:8 row_mask:0xf bank_mask:0xf
	v_cndmask_b32_dpp v203, v141, v145, vcc row_ror:8 row_mask:0xf bank_mask:0xf
	global_store_dwordx4 v[224:225], v[200:203], off
	v_cndmask_b32_dpp v250, v130, v134, vcc row_ror:8 row_mask:0xf bank_mask:0xf
	v_cndmask_b32_dpp v251, v131, v135, vcc row_ror:8 row_mask:0xf bank_mask:0xf
	v_cndmask_b32_dpp v252, v132, v136, vcc row_ror:8 row_mask:0xf bank_mask:0xf
	v_cndmask_b32_dpp v253, v133, v137, vcc row_ror:8 row_mask:0xf bank_mask:0xf
	global_store_dwordx4 v[224:225], v[250:253], off offset:512
	s_not_b64 vcc, vcc
	v_cndmask_b32_dpp v200, v142, v138, vcc row_ror:8 row_mask:0xf bank_mask:0xf
	v_cndmask_b32_dpp v201, v143, v139, vcc row_ror:8 row_mask:0xf bank_mask:0xf
	v_cndmask_b32_dpp v202, v144, v140, vcc row_ror:8 row_mask:0xf bank_mask:0xf
	v_cndmask_b32_dpp v203, v145, v141, vcc row_ror:8 row_mask:0xf bank_mask:0xf
	global_store_dwordx4 v[234:235], v[200:203], off
	v_cndmask_b32_dpp v250, v134, v130, vcc row_ror:8 row_mask:0xf bank_mask:0xf
	v_cndmask_b32_dpp v251, v135, v131, vcc row_ror:8 row_mask:0xf bank_mask:0xf
	v_cndmask_b32_dpp v252, v136, v132, vcc row_ror:8 row_mask:0xf bank_mask:0xf
	v_cndmask_b32_dpp v253, v137, v133, vcc row_ror:8 row_mask:0xf bank_mask:0xf
	global_store_dwordx4 v[234:235], v[250:253], off offset:512
	s_not_b64 vcc, vcc
	v_mul_f32_e32 v196, v142, v142
	v_mul_f32_e32 v197, v143, v143
	v_fmac_f32_e32 v196, v144, v144
	v_fmac_f32_e32 v197, v145, v145
	v_fmac_f32_e32 v196, v138, v138
	v_fmac_f32_e32 v197, v139, v139
	v_fmac_f32_e32 v196, v140, v140
	v_fmac_f32_e32 v197, v141, v141
	v_fmac_f32_e32 v196, v134, v134
	v_fmac_f32_e32 v197, v135, v135
	v_fmac_f32_e32 v196, v136, v136
	v_fmac_f32_e32 v197, v137, v137
	v_fmac_f32_e32 v196, v130, v130
	v_fmac_f32_e32 v197, v131, v131
	v_fmac_f32_e32 v196, v132, v132
	v_fmac_f32_e32 v197, v133, v133
	v_add_f32_e32 v198, v196, v197
	ds_bpermute_b32 v199, v194, v198
	s_mov_b32 s34, 0x0
	v_lshl_add_u64 v[234:235], v[228:229], 0, s[34:35]
	v_pk_mul_f32 v[200:201], v[142:143], v[56:57]
	v_pk_mul_f32 v[202:203], v[144:145], v[58:59]
	v_pk_mul_f32 v[204:205], v[138:139], v[60:61]
	v_pk_mul_f32 v[236:237], v[140:141], v[62:63]
	v_cvt_pk_bf16_f32 v250, v200, v201
	v_cvt_pk_bf16_f32 v251, v202, v203
	v_cvt_pk_bf16_f32 v252, v204, v205
	v_cvt_pk_bf16_f32 v253, v236, v237
	global_store_dwordx4 v[234:235], v[250:253], off
	s_waitcnt lgkmcnt(0)
; __device__ __forceinline__ unsigned cvt_pk_bf16(float lo, float hi) { unsigned r; asm volatile("v_cvt_pk_bf16_f32 %0, %1, %2" : "=v"(r) : "v"(lo), "v"(hi)); return r; }
;     __device__ __forceinline__ void operator()(const f32x4 (&acc)[2][2][4][2], const Unit& u, int wr, int wc, int fr, int fq) const {
;     ...
;             for (int m = 0; m < 4; ++m) { const int row = row0 + ai * HALF + m * 16; const size_t off = (size_t)row * ldc + col0; float ss = 0.f;
; #pragma unroll
;                 for (int bj = 0; bj < 2; ++bj) {
;                     const f32x4 x0 = rb[m][bj][0] + acc[ai][bj][m][0], x1 = rb[m][bj][1] + acc[ai][bj][m][1];
;                     if (out) { *(f32x4*)(out + off + bj * HALF) = x0; *(f32x4*)(out + off + bj * HALF + 4) = x1; }
;                     ss += (x0[0] * x0[0] + x0[1] * x0[1]) + (x0[2] * x0[2] + x0[3] * x0[3]) + (x1[0] * x1[0] + x1[1] * x1[1]) + (x1[2] * x1[2] + x1[3] * x1[3]);
;                     const f32x4 y0 = x0 * gv[bj][0], y1 = x1 * gv[bj][1];
;                     u32x4 w; w.x = cvt_pk_bf16(y0[0], y0[1]); w.y = cvt_pk_bf16(y0[2], y0[3]); w.z = cvt_pk_bf16(y1[0], y1[1]); w.w = cvt_pk_bf16(y1[2], y1[3]);
;                     *(u32x4*)(XG + off + bj * HALF) = w; }
;                 ss += __shfl_xor(ss, 16); ss += __shfl_xor(ss, 32);
;                 if (fq == 0) SS[(size_t)row * 32 + u.pn * 4 + wc] = ss; }
	v_add_f32_e32 v198, v198, v199
	ds_bpermute_b32 v199, v195, v198
	v_pk_mul_f32 v[200:201], v[134:135], v[64:65]
	v_pk_mul_f32 v[202:203], v[136:137], v[66:67]
	v_pk_mul_f32 v[204:205], v[130:131], v[68:69]
	v_pk_mul_f32 v[236:237], v[132:133], v[70:71]
	v_cvt_pk_bf16_f32 v250, v200, v201
	v_cvt_pk_bf16_f32 v251, v202, v203
	v_cvt_pk_bf16_f32 v252, v204, v205
	v_cvt_pk_bf16_f32 v253, v236, v237
	global_store_dwordx4 v[234:235], v[250:253], off offset:256
	s_mov_b32 s34, 0x0
	v_lshl_add_u64 v[224:225], v[226:227], 0, s[34:35]
	s_waitcnt lgkmcnt(0)
	v_add_f32_e32 v198, v198, v199
	s_mov_b64 exec, s[4:5]
	global_store_dword v[224:225], v198, off
	s_mov_b64 exec, -1
	s_waitcnt vmcnt(15)
	v_pk_add_f32 v[124:125], v[124:125], v[162:163]
	v_pk_add_f32 v[126:127], v[126:127], v[164:165]
	v_pk_add_f32 v[120:121], v[120:121], v[166:167]
	v_pk_add_f32 v[122:123], v[122:123], v[168:169]
	v_pk_add_f32 v[116:117], v[116:117], v[170:171]
	v_pk_add_f32 v[118:119], v[118:119], v[172:173]
	v_pk_add_f32 v[112:113], v[112:113], v[174:175]
	v_pk_add_f32 v[114:115], v[114:115], v[176:177]
	s_mov_b32 s34, 0x100000
	v_lshl_add_u64 v[224:225], v[220:221], 0, s[34:35]
	global_load_dwordx4 v[162:165], v[224:225], off
	global_load_dwordx4 v[166:169], v[224:225], off offset:16
	global_load_dwordx4 v[170:173], v[224:225], off offset:512
	global_load_dwordx4 v[174:177], v[224:225], off offset:528
	s_mov_b32 s34, 0x20000
	v_lshl_add_u64 v[224:225], v[220:221], 0, s[34:35]
	v_lshl_add_u64 v[224:225], v[224:225], 0, s[40:41]
	v_lshl_add_u64 v[234:235], v[224:225], 0, v[222:223]
	v_lshl_add_u64 v[224:225], v[224:225], 0, v[218:219]
	v_cndmask_b32_dpp v200, v120, v124, vcc row_ror:8 row_mask:0xf bank_mask:0xf
	v_cndmask_b32_dpp v201, v121, v125, vcc row_ror:8 row_mask:0xf bank_mask:0xf
	v_cndmask_b32_dpp v202, v122, v126, vcc row_ror:8 row_mask:0xf bank_mask:0xf
	v_cndmask_b32_dpp v203, v123, v127, vcc row_ror:8 row_mask:0xf bank_mask:0xf
	global_store_dwordx4 v[224:225], v[200:203], off
	v_cndmask_b32_dpp v250, v112, v116, vcc row_ror:8 row_mask:0xf bank_mask:0xf
	v_cndmask_b32_dpp v251, v113, v117, vcc row_ror:8 row_mask:0xf bank_mask:0xf
	v_cndmask_b32_dpp v252, v114, v118, vcc row_ror:8 row_mask:0xf bank_mask:0xf
	v_cndmask_b32_dpp v253, v115, v119, vcc row_ror:8 row_mask:0xf bank_mask:0xf
	global_store_dwordx4 v[224:225], v[250:253], off offset:512
	s_not_b64 vcc, vcc
	v_cndmask_b32_dpp v200, v124, v120, vcc row_ror:8 row_mask:0xf bank_mask:0xf
	v_cndmask_b32_dpp v201, v125, v121, vcc row_ror:8 row_mask:0xf bank_mask:0xf
	v_cndmask_b32_dpp v202, v126, v122, vcc row_ror:8 row_mask:0xf bank_mask:0xf
	v_cndmask_b32_dpp v203, v127, v123, vcc row_ror:8 row_mask:0xf bank_mask:0xf
	global_store_dwordx4 v[234:235], v[200:203], off
	v_cndmask_b32_dpp v250, v116, v112, vcc row_ror:8 row_mask:0xf bank_mask:0xf
	v_cndmask_b32_dpp v251, v117, v113, vcc row_ror:8 row_mask:0xf bank_mask:0xf
	v_cndmask_b32_dpp v252, v118, v114, vcc row_ror:8 row_mask:0xf bank_mask:0xf
	v_cndmask_b32_dpp v253, v119, v115, vcc row_ror:8 row_mask:0xf bank_mask:0xf
	global_store_dwordx4 v[234:235], v[250:253], off offset:512
	s_not_b64 vcc, vcc
	v_mul_f32_e32 v196, v124, v124
	v_mul_f32_e32 v197, v125, v125
	v_fmac_f32_e32 v196, v126, v126
	v_fmac_f32_e32 v197, v127, v127
	v_fmac_f32_e32 v196, v120, v120
	v_fmac_f32_e32 v197, v121, v121
	v_fmac_f32_e32 v196, v122, v122
	v_fmac_f32_e32 v197, v123, v123
	v_fmac_f32_e32 v196, v116, v116
	v_fmac_f32_e32 v197, v117, v117
	v_fmac_f32_e32 v196, v118, v118
	v_fmac_f32_e32 v197, v119, v119
	v_fmac_f32_e32 v196, v112, v112
	v_fmac_f32_e32 v197, v113, v113
	v_fmac_f32_e32 v196, v114, v114
	v_fmac_f32_e32 v197, v115, v115
	v_add_f32_e32 v198, v196, v197
	ds_bpermute_b32 v199, v194, v198
	s_mov_b32 s34, 0x10000
	v_lshl_add_u64 v[234:235], v[228:229], 0, s[34:35]
	v_pk_mul_f32 v[200:201], v[124:125], v[56:57]
	v_pk_mul_f32 v[202:203], v[126:127], v[58:59]
	v_pk_mul_f32 v[204:205], v[120:121], v[60:61]
	v_pk_mul_f32 v[236:237], v[122:123], v[62:63]
	v_cvt_pk_bf16_f32 v250, v200, v201
	v_cvt_pk_bf16_f32 v251, v202, v203
	v_cvt_pk_bf16_f32 v252, v204, v205
	v_cvt_pk_bf16_f32 v253, v236, v237
	global_store_dwordx4 v[234:235], v[250:253], off
	s_waitcnt lgkmcnt(0)
	v_add_f32_e32 v198, v198, v199
	ds_bpermute_b32 v199, v195, v198
	v_pk_mul_f32 v[200:201], v[116:117], v[64:65]
	v_pk_mul_f32 v[202:203], v[118:119], v[66:67]
	v_pk_mul_f32 v[204:205], v[112:113], v[68:69]
	v_pk_mul_f32 v[236:237], v[114:115], v[70:71]
	v_cvt_pk_bf16_f32 v250, v200, v201
	v_cvt_pk_bf16_f32 v251, v202, v203
	v_cvt_pk_bf16_f32 v252, v204, v205
	v_cvt_pk_bf16_f32 v253, v236, v237
	global_store_dwordx4 v[234:235], v[250:253], off offset:256
	s_mov_b32 s34, 0x800
	v_lshl_add_u64 v[224:225], v[226:227], 0, s[34:35]
	s_waitcnt lgkmcnt(0)
	v_add_f32_e32 v198, v198, v199
	s_mov_b64 exec, s[4:5]
	global_store_dword v[224:225], v198, off
	s_mov_b64 exec, -1
	s_waitcnt vmcnt(22)
; __device__ __forceinline__ unsigned cvt_pk_bf16(float lo, float hi) { unsigned r; asm volatile("v_cvt_pk_bf16_f32 %0, %1, %2" : "=v"(r) : "v"(lo), "v"(hi)); return r; }
;     __device__ __forceinline__ void operator()(const f32x4 (&acc)[2][2][4][2], const Unit& u, int wr, int wc, int fr, int fq) const {
;     ...
;             for (int m = 0; m < 4; ++m) { const int row = row0 + ai * HALF + m * 16; const size_t off = (size_t)row * ldc + col0; float ss = 0.f;
; #pragma unroll
;                 for (int bj = 0; bj < 2; ++bj) {
;                     const f32x4 x0 = rb[m][bj][0] + acc[ai][bj][m][0], x1 = rb[m][bj][1] + acc[ai][bj][m][1];
;                     if (out) { *(f32x4*)(out + off + bj * HALF) = x0; *(f32x4*)(out + off + bj * HALF + 4) = x1; }
;                     ss += (x0[0] * x0[0] + x0[1] * x0[1]) + (x0[2] * x0[2] + x0[3] * x0[3]) + (x1[0] * x1[0] + x1[1] * x1[1]) + (x1[2] * x1[2] + x1[3] * x1[3]);
;                     const f32x4 y0 = x0 * gv[bj][0], y1 = x1 * gv[bj][1];
;                     u32x4 w; w.x = cvt_pk_bf16(y0[0], y0[1]); w.y = cvt_pk_bf16(y0[2], y0[3]); w.z = cvt_pk_bf16(y1[0], y1[1]); w.w = cvt_pk_bf16(y1[2], y1[3]);
;                     *(u32x4*)(XG + off + bj * HALF) = w; }
;                 ss += __shfl_xor(ss, 16); ss += __shfl_xor(ss, 32);
;                 if (fq == 0) SS[(size_t)row * 32 + u.pn * 4 + wc] = ss; }
	v_pk_add_f32 v[108:109], v[108:109], v[178:179]
	v_pk_add_f32 v[110:111], v[110:111], v[180:181]
	v_pk_add_f32 v[104:105], v[104:105], v[182:183]
	v_pk_add_f32 v[106:107], v[106:107], v[184:185]
	v_pk_add_f32 v[100:101], v[100:101], v[186:187]
	v_pk_add_f32 v[102:103], v[102:103], v[188:189]
	v_pk_add_f32 v[96:97], v[96:97], v[190:191]
	v_pk_add_f32 v[98:99], v[98:99], v[192:193]
	s_mov_b32 s34, 0x120000
	v_lshl_add_u64 v[224:225], v[220:221], 0, s[34:35]
	global_load_dwordx4 v[178:181], v[224:225], off
	global_load_dwordx4 v[182:185], v[224:225], off offset:16
	global_load_dwordx4 v[186:189], v[224:225], off offset:512
	global_load_dwordx4 v[190:193], v[224:225], off offset:528
	s_mov_b32 s34, 0x40000
	v_lshl_add_u64 v[224:225], v[220:221], 0, s[34:35]
	v_lshl_add_u64 v[224:225], v[224:225], 0, s[40:41]
	v_lshl_add_u64 v[234:235], v[224:225], 0, v[222:223]
	v_lshl_add_u64 v[224:225], v[224:225], 0, v[218:219]
	v_cndmask_b32_dpp v200, v104, v108, vcc row_ror:8 row_mask:0xf bank_mask:0xf
	v_cndmask_b32_dpp v201, v105, v109, vcc row_ror:8 row_mask:0xf bank_mask:0xf
	v_cndmask_b32_dpp v202, v106, v110, vcc row_ror:8 row_mask:0xf bank_mask:0xf
	v_cndmask_b32_dpp v203, v107, v111, vcc row_ror:8 row_mask:0xf bank_mask:0xf
	global_store_dwordx4 v[224:225], v[200:203], off
	v_cndmask_b32_dpp v250, v96, v100, vcc row_ror:8 row_mask:0xf bank_mask:0xf
	v_cndmask_b32_dpp v251, v97, v101, vcc row_ror:8 row_mask:0xf bank_mask:0xf
	v_cndmask_b32_dpp v252, v98, v102, vcc row_ror:8 row_mask:0xf bank_mask:0xf
	v_cndmask_b32_dpp v253, v99, v103, vcc row_ror:8 row_mask:0xf bank_mask:0xf
	global_store_dwordx4 v[224:225], v[250:253], off offset:512
	s_not_b64 vcc, vcc
	v_cndmask_b32_dpp v200, v108, v104, vcc row_ror:8 row_mask:0xf bank_mask:0xf
	v_cndmask_b32_dpp v201, v109, v105, vcc row_ror:8 row_mask:0xf bank_mask:0xf
	v_cndmask_b32_dpp v202, v110, v106, vcc row_ror:8 row_mask:0xf bank_mask:0xf
	v_cndmask_b32_dpp v203, v111, v107, vcc row_ror:8 row_mask:0xf bank_mask:0xf
	global_store_dwordx4 v[234:235], v[200:203], off
	v_cndmask_b32_dpp v250, v100, v96, vcc row_ror:8 row_mask:0xf bank_mask:0xf
	v_cndmask_b32_dpp v251, v101, v97, vcc row_ror:8 row_mask:0xf bank_mask:0xf
	v_cndmask_b32_dpp v252, v102, v98, vcc row_ror:8 row_mask:0xf bank_mask:0xf
	v_cndmask_b32_dpp v253, v103, v99, vcc row_ror:8 row_mask:0xf bank_mask:0xf
	global_store_dwordx4 v[234:235], v[250:253], off offset:512
	s_not_b64 vcc, vcc
	v_mul_f32_e32 v196, v108, v108
	v_mul_f32_e32 v197, v109, v109
	v_fmac_f32_e32 v196, v110, v110
	v_fmac_f32_e32 v197, v111, v111
	v_fmac_f32_e32 v196, v104, v104
	v_fmac_f32_e32 v197, v105, v105
	v_fmac_f32_e32 v196, v106, v106
	v_fmac_f32_e32 v197, v107, v107
	v_fmac_f32_e32 v196, v100, v100
	v_fmac_f32_e32 v197, v101, v101
	v_fmac_f32_e32 v196, v102, v102
	v_fmac_f32_e32 v197, v103, v103
	v_fmac_f32_e32 v196, v96, v96
	v_fmac_f32_e32 v197, v97, v97
	v_fmac_f32_e32 v196, v98, v98
	v_fmac_f32_e32 v197, v99, v99
	v_add_f32_e32 v198, v196, v197
	ds_bpermute_b32 v199, v194, v198
	s_mov_b32 s34, 0x20000
	v_lshl_add_u64 v[234:235], v[228:229], 0, s[34:35]
	v_pk_mul_f32 v[200:201], v[108:109], v[56:57]
	v_pk_mul_f32 v[202:203], v[110:111], v[58:59]
	v_pk_mul_f32 v[204:205], v[104:105], v[60:61]
	v_pk_mul_f32 v[236:237], v[106:107], v[62:63]
	v_cvt_pk_bf16_f32 v250, v200, v201
	v_cvt_pk_bf16_f32 v251, v202, v203
	v_cvt_pk_bf16_f32 v252, v204, v205
	v_cvt_pk_bf16_f32 v253, v236, v237
	global_store_dwordx4 v[234:235], v[250:253], off
	s_waitcnt lgkmcnt(0)
	v_add_f32_e32 v198, v198, v199
	ds_bpermute_b32 v199, v195, v198
	v_pk_mul_f32 v[200:201], v[100:101], v[64:65]
	v_pk_mul_f32 v[202:203], v[102:103], v[66:67]
	v_pk_mul_f32 v[204:205], v[96:97], v[68:69]
	v_pk_mul_f32 v[236:237], v[98:99], v[70:71]
	v_cvt_pk_bf16_f32 v250, v200, v201
	v_cvt_pk_bf16_f32 v251, v202, v203
	v_cvt_pk_bf16_f32 v252, v204, v205
	v_cvt_pk_bf16_f32 v253, v236, v237
	global_store_dwordx4 v[234:235], v[250:253], off offset:256
	s_mov_b32 s34, 0x1000
	v_lshl_add_u64 v[224:225], v[226:227], 0, s[34:35]
	s_waitcnt lgkmcnt(0)
	v_add_f32_e32 v198, v198, v199
	s_mov_b64 exec, s[4:5]
	global_store_dword v[224:225], v198, off
	s_mov_b64 exec, -1
	s_waitcnt vmcnt(29)
	v_pk_add_f32 v[92:93], v[92:93], v[146:147]
	v_pk_add_f32 v[94:95], v[94:95], v[148:149]
	v_pk_add_f32 v[88:89], v[88:89], v[150:151]
	v_pk_add_f32 v[90:91], v[90:91], v[152:153]
	v_pk_add_f32 v[84:85], v[84:85], v[154:155]
	v_pk_add_f32 v[86:87], v[86:87], v[156:157]
	v_pk_add_f32 v[80:81], v[80:81], v[158:159]
	v_pk_add_f32 v[82:83], v[82:83], v[160:161]
	s_mov_b32 s34, 0x140000
	v_lshl_add_u64 v[224:225], v[220:221], 0, s[34:35]
	global_load_dwordx4 v[146:149], v[224:225], off
	global_load_dwordx4 v[150:153], v[224:225], off offset:16
	global_load_dwordx4 v[154:157], v[224:225], off offset:512
	global_load_dwordx4 v[158:161], v[224:225], off offset:528
	s_mov_b32 s34, 0x60000
	v_lshl_add_u64 v[224:225], v[220:221], 0, s[34:35]
	v_lshl_add_u64 v[224:225], v[224:225], 0, s[40:41]
	v_lshl_add_u64 v[234:235], v[224:225], 0, v[222:223]
	v_lshl_add_u64 v[224:225], v[224:225], 0, v[218:219]
	v_cndmask_b32_dpp v200, v88, v92, vcc row_ror:8 row_mask:0xf bank_mask:0xf
	v_cndmask_b32_dpp v201, v89, v93, vcc row_ror:8 row_mask:0xf bank_mask:0xf
	v_cndmask_b32_dpp v202, v90, v94, vcc row_ror:8 row_mask:0xf bank_mask:0xf
	v_cndmask_b32_dpp v203, v91, v95, vcc row_ror:8 row_mask:0xf bank_mask:0xf
	global_store_dwordx4 v[224:225], v[200:203], off
	v_cndmask_b32_dpp v250, v80, v84, vcc row_ror:8 row_mask:0xf bank_mask:0xf
	v_cndmask_b32_dpp v251, v81, v85, vcc row_ror:8 row_mask:0xf bank_mask:0xf
	v_cndmask_b32_dpp v252, v82, v86, vcc row_ror:8 row_mask:0xf bank_mask:0xf
; __device__ __forceinline__ unsigned cvt_pk_bf16(float lo, float hi) { unsigned r; asm volatile("v_cvt_pk_bf16_f32 %0, %1, %2" : "=v"(r) : "v"(lo), "v"(hi)); return r; }
;     __device__ __forceinline__ void operator()(const f32x4 (&acc)[2][2][4][2], const Unit& u, int wr, int wc, int fr, int fq) const {
;     ...
;             for (int m = 0; m < 4; ++m) { const int row = row0 + ai * HALF + m * 16; const size_t off = (size_t)row * ldc + col0; float ss = 0.f;
; #pragma unroll
;                 for (int bj = 0; bj < 2; ++bj) {
;                     const f32x4 x0 = rb[m][bj][0] + acc[ai][bj][m][0], x1 = rb[m][bj][1] + acc[ai][bj][m][1];
;                     if (out) { *(f32x4*)(out + off + bj * HALF) = x0; *(f32x4*)(out + off + bj * HALF + 4) = x1; }
;                     ss += (x0[0] * x0[0] + x0[1] * x0[1]) + (x0[2] * x0[2] + x0[3] * x0[3]) + (x1[0] * x1[0] + x1[1] * x1[1]) + (x1[2] * x1[2] + x1[3] * x1[3]);
;                     const f32x4 y0 = x0 * gv[bj][0], y1 = x1 * gv[bj][1];
;                     u32x4 w; w.x = cvt_pk_bf16(y0[0], y0[1]); w.y = cvt_pk_bf16(y0[2], y0[3]); w.z = cvt_pk_bf16(y1[0], y1[1]); w.w = cvt_pk_bf16(y1[2], y1[3]);
;                     *(u32x4*)(XG + off + bj * HALF) = w; }
;                 ss += __shfl_xor(ss, 16); ss += __shfl_xor(ss, 32);
;                 if (fq == 0) SS[(size_t)row * 32 + u.pn * 4 + wc] = ss; }
	v_cndmask_b32_dpp v253, v83, v87, vcc row_ror:8 row_mask:0xf bank_mask:0xf
	global_store_dwordx4 v[224:225], v[250:253], off offset:512
	s_not_b64 vcc, vcc
	v_cndmask_b32_dpp v200, v92, v88, vcc row_ror:8 row_mask:0xf bank_mask:0xf
	v_cndmask_b32_dpp v201, v93, v89, vcc row_ror:8 row_mask:0xf bank_mask:0xf
	v_cndmask_b32_dpp v202, v94, v90, vcc row_ror:8 row_mask:0xf bank_mask:0xf
	v_cndmask_b32_dpp v203, v95, v91, vcc row_ror:8 row_mask:0xf bank_mask:0xf
	global_store_dwordx4 v[234:235], v[200:203], off
	v_cndmask_b32_dpp v250, v84, v80, vcc row_ror:8 row_mask:0xf bank_mask:0xf
	v_cndmask_b32_dpp v251, v85, v81, vcc row_ror:8 row_mask:0xf bank_mask:0xf
	v_cndmask_b32_dpp v252, v86, v82, vcc row_ror:8 row_mask:0xf bank_mask:0xf
	v_cndmask_b32_dpp v253, v87, v83, vcc row_ror:8 row_mask:0xf bank_mask:0xf
	global_store_dwordx4 v[234:235], v[250:253], off offset:512
	s_not_b64 vcc, vcc
	v_mul_f32_e32 v196, v92, v92
	v_mul_f32_e32 v197, v93, v93
	v_fmac_f32_e32 v196, v94, v94
	v_fmac_f32_e32 v197, v95, v95
	v_fmac_f32_e32 v196, v88, v88
	v_fmac_f32_e32 v197, v89, v89
	v_fmac_f32_e32 v196, v90, v90
	v_fmac_f32_e32 v197, v91, v91
	v_fmac_f32_e32 v196, v84, v84
	v_fmac_f32_e32 v197, v85, v85
	v_fmac_f32_e32 v196, v86, v86
	v_fmac_f32_e32 v197, v87, v87
	v_fmac_f32_e32 v196, v80, v80
	v_fmac_f32_e32 v197, v81, v81
	v_fmac_f32_e32 v196, v82, v82
	v_fmac_f32_e32 v197, v83, v83
	v_add_f32_e32 v198, v196, v197
	ds_bpermute_b32 v199, v194, v198
	s_mov_b32 s34, 0x30000
	v_lshl_add_u64 v[234:235], v[228:229], 0, s[34:35]
	v_pk_mul_f32 v[200:201], v[92:93], v[56:57]
	v_pk_mul_f32 v[202:203], v[94:95], v[58:59]
	v_pk_mul_f32 v[204:205], v[88:89], v[60:61]
	v_pk_mul_f32 v[236:237], v[90:91], v[62:63]
	v_cvt_pk_bf16_f32 v250, v200, v201
	v_cvt_pk_bf16_f32 v251, v202, v203
	v_cvt_pk_bf16_f32 v252, v204, v205
	v_cvt_pk_bf16_f32 v253, v236, v237
	global_store_dwordx4 v[234:235], v[250:253], off
	s_waitcnt lgkmcnt(0)
	v_add_f32_e32 v198, v198, v199
	ds_bpermute_b32 v199, v195, v198
	v_pk_mul_f32 v[200:201], v[84:85], v[64:65]
	v_pk_mul_f32 v[202:203], v[86:87], v[66:67]
	v_pk_mul_f32 v[204:205], v[80:81], v[68:69]
	v_pk_mul_f32 v[236:237], v[82:83], v[70:71]
	v_cvt_pk_bf16_f32 v250, v200, v201
	v_cvt_pk_bf16_f32 v251, v202, v203
	v_cvt_pk_bf16_f32 v252, v204, v205
	v_cvt_pk_bf16_f32 v253, v236, v237
	global_store_dwordx4 v[234:235], v[250:253], off offset:256
	s_mov_b32 s34, 0x1800
	v_lshl_add_u64 v[224:225], v[226:227], 0, s[34:35]
	s_waitcnt lgkmcnt(0)
	v_add_f32_e32 v198, v198, v199
	s_mov_b64 exec, s[4:5]
	global_store_dword v[224:225], v198, off
	s_mov_b64 exec, -1
	s_waitcnt vmcnt(29)
	v_pk_add_f32 v[76:77], v[76:77], v[162:163]
	v_pk_add_f32 v[78:79], v[78:79], v[164:165]
	v_pk_add_f32 v[72:73], v[72:73], v[166:167]
	v_pk_add_f32 v[74:75], v[74:75], v[168:169]
	v_pk_add_f32 v[52:53], v[52:53], v[170:171]
	v_pk_add_f32 v[54:55], v[54:55], v[172:173]
	v_pk_add_f32 v[48:49], v[48:49], v[174:175]
	v_pk_add_f32 v[50:51], v[50:51], v[176:177]
	s_mov_b32 s34, 0x160000
	v_lshl_add_u64 v[224:225], v[220:221], 0, s[34:35]
	global_load_dwordx4 v[162:165], v[224:225], off
	global_load_dwordx4 v[166:169], v[224:225], off offset:16
	global_load_dwordx4 v[170:173], v[224:225], off offset:512
	global_load_dwordx4 v[174:177], v[224:225], off offset:528
	s_mov_b32 s34, 0x100000
	v_lshl_add_u64 v[224:225], v[220:221], 0, s[34:35]
	v_lshl_add_u64 v[224:225], v[224:225], 0, s[40:41]
	v_lshl_add_u64 v[234:235], v[224:225], 0, v[222:223]
	v_lshl_add_u64 v[224:225], v[224:225], 0, v[218:219]
	v_cndmask_b32_dpp v200, v72, v76, vcc row_ror:8 row_mask:0xf bank_mask:0xf
	v_cndmask_b32_dpp v201, v73, v77, vcc row_ror:8 row_mask:0xf bank_mask:0xf
	v_cndmask_b32_dpp v202, v74, v78, vcc row_ror:8 row_mask:0xf bank_mask:0xf
	v_cndmask_b32_dpp v203, v75, v79, vcc row_ror:8 row_mask:0xf bank_mask:0xf
	global_store_dwordx4 v[224:225], v[200:203], off
	v_cndmask_b32_dpp v250, v48, v52, vcc row_ror:8 row_mask:0xf bank_mask:0xf
	v_cndmask_b32_dpp v251, v49, v53, vcc row_ror:8 row_mask:0xf bank_mask:0xf
	v_cndmask_b32_dpp v252, v50, v54, vcc row_ror:8 row_mask:0xf bank_mask:0xf
	v_cndmask_b32_dpp v253, v51, v55, vcc row_ror:8 row_mask:0xf bank_mask:0xf
	global_store_dwordx4 v[224:225], v[250:253], off offset:512
	s_not_b64 vcc, vcc
	v_cndmask_b32_dpp v200, v76, v72, vcc row_ror:8 row_mask:0xf bank_mask:0xf
	v_cndmask_b32_dpp v201, v77, v73, vcc row_ror:8 row_mask:0xf bank_mask:0xf
	v_cndmask_b32_dpp v202, v78, v74, vcc row_ror:8 row_mask:0xf bank_mask:0xf
	v_cndmask_b32_dpp v203, v79, v75, vcc row_ror:8 row_mask:0xf bank_mask:0xf
	global_store_dwordx4 v[234:235], v[200:203], off
	v_cndmask_b32_dpp v250, v52, v48, vcc row_ror:8 row_mask:0xf bank_mask:0xf
	v_cndmask_b32_dpp v251, v53, v49, vcc row_ror:8 row_mask:0xf bank_mask:0xf
	v_cndmask_b32_dpp v252, v54, v50, vcc row_ror:8 row_mask:0xf bank_mask:0xf
	v_cndmask_b32_dpp v253, v55, v51, vcc row_ror:8 row_mask:0xf bank_mask:0xf
	global_store_dwordx4 v[234:235], v[250:253], off offset:512
	s_not_b64 vcc, vcc
	v_mul_f32_e32 v196, v76, v76
	v_mul_f32_e32 v197, v77, v77
	v_fmac_f32_e32 v196, v78, v78
	v_fmac_f32_e32 v197, v79, v79
	v_fmac_f32_e32 v196, v72, v72
	v_fmac_f32_e32 v197, v73, v73
	v_fmac_f32_e32 v196, v74, v74
	v_fmac_f32_e32 v197, v75, v75
	v_fmac_f32_e32 v196, v52, v52
	v_fmac_f32_e32 v197, v53, v53
	v_fmac_f32_e32 v196, v54, v54
	v_fmac_f32_e32 v197, v55, v55
	v_fmac_f32_e32 v196, v48, v48
	v_fmac_f32_e32 v197, v49, v49
	v_fmac_f32_e32 v196, v50, v50
	v_fmac_f32_e32 v197, v51, v51
	v_add_f32_e32 v198, v196, v197
	ds_bpermute_b32 v199, v194, v198
	s_mov_b32 s34, 0x80000
	v_lshl_add_u64 v[234:235], v[228:229], 0, s[34:35]
	v_pk_mul_f32 v[200:201], v[76:77], v[56:57]
	v_pk_mul_f32 v[202:203], v[78:79], v[58:59]
	v_pk_mul_f32 v[204:205], v[72:73], v[60:61]
	v_pk_mul_f32 v[236:237], v[74:75], v[62:63]
	v_cvt_pk_bf16_f32 v250, v200, v201
	v_cvt_pk_bf16_f32 v251, v202, v203
	v_cvt_pk_bf16_f32 v252, v204, v205
	v_cvt_pk_bf16_f32 v253, v236, v237
	global_store_dwordx4 v[234:235], v[250:253], off
	s_waitcnt lgkmcnt(0)
; __device__ __forceinline__ unsigned cvt_pk_bf16(float lo, float hi) { unsigned r; asm volatile("v_cvt_pk_bf16_f32 %0, %1, %2" : "=v"(r) : "v"(lo), "v"(hi)); return r; }
;     __device__ __forceinline__ void operator()(const f32x4 (&acc)[2][2][4][2], const Unit& u, int wr, int wc, int fr, int fq) const {
;     ...
;             for (int m = 0; m < 4; ++m) { const int row = row0 + ai * HALF + m * 16; const size_t off = (size_t)row * ldc + col0; float ss = 0.f;
; #pragma unroll
;                 for (int bj = 0; bj < 2; ++bj) {
;                     const f32x4 x0 = rb[m][bj][0] + acc[ai][bj][m][0], x1 = rb[m][bj][1] + acc[ai][bj][m][1];
;                     if (out) { *(f32x4*)(out + off + bj * HALF) = x0; *(f32x4*)(out + off + bj * HALF + 4) = x1; }
;                     ss += (x0[0] * x0[0] + x0[1] * x0[1]) + (x0[2] * x0[2] + x0[3] * x0[3]) + (x1[0] * x1[0] + x1[1] * x1[1]) + (x1[2] * x1[2] + x1[3] * x1[3]);
;                     const f32x4 y0 = x0 * gv[bj][0], y1 = x1 * gv[bj][1];
;                     u32x4 w; w.x = cvt_pk_bf16(y0[0], y0[1]); w.y = cvt_pk_bf16(y0[2], y0[3]); w.z = cvt_pk_bf16(y1[0], y1[1]); w.w = cvt_pk_bf16(y1[2], y1[3]);
;                     *(u32x4*)(XG + off + bj * HALF) = w; }
;                 ss += __shfl_xor(ss, 16); ss += __shfl_xor(ss, 32);
;                 if (fq == 0) SS[(size_t)row * 32 + u.pn * 4 + wc] = ss; }
	v_add_f32_e32 v198, v198, v199
	ds_bpermute_b32 v199, v195, v198
	v_pk_mul_f32 v[200:201], v[52:53], v[64:65]
	v_pk_mul_f32 v[202:203], v[54:55], v[66:67]
	v_pk_mul_f32 v[204:205], v[48:49], v[68:69]
	v_pk_mul_f32 v[236:237], v[50:51], v[70:71]
	v_cvt_pk_bf16_f32 v250, v200, v201
	v_cvt_pk_bf16_f32 v251, v202, v203
	v_cvt_pk_bf16_f32 v252, v204, v205
	v_cvt_pk_bf16_f32 v253, v236, v237
	global_store_dwordx4 v[234:235], v[250:253], off offset:256
	s_mov_b32 s34, 0x4000
	v_lshl_add_u64 v[224:225], v[226:227], 0, s[34:35]
	s_waitcnt lgkmcnt(0)
	v_add_f32_e32 v198, v198, v199
	s_mov_b64 exec, s[4:5]
	global_store_dword v[224:225], v198, off
	s_mov_b64 exec, -1
	s_waitcnt vmcnt(29)
	v_pk_add_f32 v[44:45], v[44:45], v[178:179]
	v_pk_add_f32 v[46:47], v[46:47], v[180:181]
	v_pk_add_f32 v[40:41], v[40:41], v[182:183]
	v_pk_add_f32 v[42:43], v[42:43], v[184:185]
	v_pk_add_f32 v[36:37], v[36:37], v[186:187]
	v_pk_add_f32 v[38:39], v[38:39], v[188:189]
	v_pk_add_f32 v[32:33], v[32:33], v[190:191]
	v_pk_add_f32 v[34:35], v[34:35], v[192:193]
	s_mov_b32 s34, 0x120000
	v_lshl_add_u64 v[224:225], v[220:221], 0, s[34:35]
	v_lshl_add_u64 v[224:225], v[224:225], 0, s[40:41]
	v_lshl_add_u64 v[234:235], v[224:225], 0, v[222:223]
	v_lshl_add_u64 v[224:225], v[224:225], 0, v[218:219]
	v_cndmask_b32_dpp v200, v40, v44, vcc row_ror:8 row_mask:0xf bank_mask:0xf
	v_cndmask_b32_dpp v201, v41, v45, vcc row_ror:8 row_mask:0xf bank_mask:0xf
	v_cndmask_b32_dpp v202, v42, v46, vcc row_ror:8 row_mask:0xf bank_mask:0xf
	v_cndmask_b32_dpp v203, v43, v47, vcc row_ror:8 row_mask:0xf bank_mask:0xf
	global_store_dwordx4 v[224:225], v[200:203], off
	v_cndmask_b32_dpp v250, v32, v36, vcc row_ror:8 row_mask:0xf bank_mask:0xf
	v_cndmask_b32_dpp v251, v33, v37, vcc row_ror:8 row_mask:0xf bank_mask:0xf
	v_cndmask_b32_dpp v252, v34, v38, vcc row_ror:8 row_mask:0xf bank_mask:0xf
	v_cndmask_b32_dpp v253, v35, v39, vcc row_ror:8 row_mask:0xf bank_mask:0xf
	global_store_dwordx4 v[224:225], v[250:253], off offset:512
	s_not_b64 vcc, vcc
	v_cndmask_b32_dpp v200, v44, v40, vcc row_ror:8 row_mask:0xf bank_mask:0xf
	v_cndmask_b32_dpp v201, v45, v41, vcc row_ror:8 row_mask:0xf bank_mask:0xf
	v_cndmask_b32_dpp v202, v46, v42, vcc row_ror:8 row_mask:0xf bank_mask:0xf
	v_cndmask_b32_dpp v203, v47, v43, vcc row_ror:8 row_mask:0xf bank_mask:0xf
	global_store_dwordx4 v[234:235], v[200:203], off
	v_cndmask_b32_dpp v250, v36, v32, vcc row_ror:8 row_mask:0xf bank_mask:0xf
	v_cndmask_b32_dpp v251, v37, v33, vcc row_ror:8 row_mask:0xf bank_mask:0xf
	v_cndmask_b32_dpp v252, v38, v34, vcc row_ror:8 row_mask:0xf bank_mask:0xf
	v_cndmask_b32_dpp v253, v39, v35, vcc row_ror:8 row_mask:0xf bank_mask:0xf
	global_store_dwordx4 v[234:235], v[250:253], off offset:512
	s_not_b64 vcc, vcc
	v_mul_f32_e32 v196, v44, v44
	v_mul_f32_e32 v197, v45, v45
	v_fmac_f32_e32 v196, v46, v46
	v_fmac_f32_e32 v197, v47, v47
	v_fmac_f32_e32 v196, v40, v40
	v_fmac_f32_e32 v197, v41, v41
	v_fmac_f32_e32 v196, v42, v42
	v_fmac_f32_e32 v197, v43, v43
	v_fmac_f32_e32 v196, v36, v36
	v_fmac_f32_e32 v197, v37, v37
	v_fmac_f32_e32 v196, v38, v38
	v_fmac_f32_e32 v197, v39, v39
	v_fmac_f32_e32 v196, v32, v32
	v_fmac_f32_e32 v197, v33, v33
	v_fmac_f32_e32 v196, v34, v34
	v_fmac_f32_e32 v197, v35, v35
	v_add_f32_e32 v198, v196, v197
	ds_bpermute_b32 v199, v194, v198
	s_mov_b32 s34, 0x90000
	v_lshl_add_u64 v[234:235], v[228:229], 0, s[34:35]
	v_pk_mul_f32 v[200:201], v[44:45], v[56:57]
	v_pk_mul_f32 v[202:203], v[46:47], v[58:59]
	v_pk_mul_f32 v[204:205], v[40:41], v[60:61]
	v_pk_mul_f32 v[236:237], v[42:43], v[62:63]
	v_cvt_pk_bf16_f32 v250, v200, v201
	v_cvt_pk_bf16_f32 v251, v202, v203
	v_cvt_pk_bf16_f32 v252, v204, v205
	v_cvt_pk_bf16_f32 v253, v236, v237
	global_store_dwordx4 v[234:235], v[250:253], off
	s_waitcnt lgkmcnt(0)
	v_add_f32_e32 v198, v198, v199
	ds_bpermute_b32 v199, v195, v198
	v_pk_mul_f32 v[200:201], v[36:37], v[64:65]
	v_pk_mul_f32 v[202:203], v[38:39], v[66:67]
	v_pk_mul_f32 v[204:205], v[32:33], v[68:69]
	v_pk_mul_f32 v[236:237], v[34:35], v[70:71]
	v_cvt_pk_bf16_f32 v250, v200, v201
	v_cvt_pk_bf16_f32 v251, v202, v203
	v_cvt_pk_bf16_f32 v252, v204, v205
	v_cvt_pk_bf16_f32 v253, v236, v237
	global_store_dwordx4 v[234:235], v[250:253], off offset:256
	s_mov_b32 s34, 0x4800
	v_lshl_add_u64 v[224:225], v[226:227], 0, s[34:35]
	s_waitcnt lgkmcnt(0)
	v_add_f32_e32 v198, v198, v199
	s_mov_b64 exec, s[4:5]
	global_store_dword v[224:225], v198, off
	s_mov_b64 exec, -1
	s_waitcnt vmcnt(25)
; __device__ __forceinline__ unsigned cvt_pk_bf16(float lo, float hi) { unsigned r; asm volatile("v_cvt_pk_bf16_f32 %0, %1, %2" : "=v"(r) : "v"(lo), "v"(hi)); return r; }
;     __device__ __forceinline__ void operator()(const f32x4 (&acc)[2][2][4][2], const Unit& u, int wr, int wc, int fr, int fq) const {
;     ...
;             for (int m = 0; m < 4; ++m) { const int row = row0 + ai * HALF + m * 16; const size_t off = (size_t)row * ldc + col0; float ss = 0.f;
; #pragma unroll
;                 for (int bj = 0; bj < 2; ++bj) {
;                     const f32x4 x0 = rb[m][bj][0] + acc[ai][bj][m][0], x1 = rb[m][bj][1] + acc[ai][bj][m][1];
;                     if (out) { *(f32x4*)(out + off + bj * HALF) = x0; *(f32x4*)(out + off + bj * HALF + 4) = x1; }
;                     ss += (x0[0] * x0[0] + x0[1] * x0[1]) + (x0[2] * x0[2] + x0[3] * x0[3]) + (x1[0] * x1[0] + x1[1] * x1[1]) + (x1[2] * x1[2] + x1[3] * x1[3]);
;                     const f32x4 y0 = x0 * gv[bj][0], y1 = x1 * gv[bj][1];
;                     u32x4 w; w.x = cvt_pk_bf16(y0[0], y0[1]); w.y = cvt_pk_bf16(y0[2], y0[3]); w.z = cvt_pk_bf16(y1[0], y1[1]); w.w = cvt_pk_bf16(y1[2], y1[3]);
;                     *(u32x4*)(XG + off + bj * HALF) = w; }
;                 ss += __shfl_xor(ss, 16); ss += __shfl_xor(ss, 32);
;                 if (fq == 0) SS[(size_t)row * 32 + u.pn * 4 + wc] = ss; }
	v_pk_add_f32 v[28:29], v[28:29], v[146:147]
	v_pk_add_f32 v[30:31], v[30:31], v[148:149]
	v_pk_add_f32 v[24:25], v[24:25], v[150:151]
	v_pk_add_f32 v[26:27], v[26:27], v[152:153]
	v_pk_add_f32 v[20:21], v[20:21], v[154:155]
	v_pk_add_f32 v[22:23], v[22:23], v[156:157]
	v_pk_add_f32 v[16:17], v[16:17], v[158:159]
	v_pk_add_f32 v[18:19], v[18:19], v[160:161]
	s_mov_b32 s34, 0x140000
	v_lshl_add_u64 v[224:225], v[220:221], 0, s[34:35]
	v_lshl_add_u64 v[224:225], v[224:225], 0, s[40:41]
	v_lshl_add_u64 v[234:235], v[224:225], 0, v[222:223]
	v_lshl_add_u64 v[224:225], v[224:225], 0, v[218:219]
	v_cndmask_b32_dpp v200, v24, v28, vcc row_ror:8 row_mask:0xf bank_mask:0xf
	v_cndmask_b32_dpp v201, v25, v29, vcc row_ror:8 row_mask:0xf bank_mask:0xf
	v_cndmask_b32_dpp v202, v26, v30, vcc row_ror:8 row_mask:0xf bank_mask:0xf
	v_cndmask_b32_dpp v203, v27, v31, vcc row_ror:8 row_mask:0xf bank_mask:0xf
	global_store_dwordx4 v[224:225], v[200:203], off
	v_cndmask_b32_dpp v250, v16, v20, vcc row_ror:8 row_mask:0xf bank_mask:0xf
	v_cndmask_b32_dpp v251, v17, v21, vcc row_ror:8 row_mask:0xf bank_mask:0xf
	v_cndmask_b32_dpp v252, v18, v22, vcc row_ror:8 row_mask:0xf bank_mask:0xf
	v_cndmask_b32_dpp v253, v19, v23, vcc row_ror:8 row_mask:0xf bank_mask:0xf
	global_store_dwordx4 v[224:225], v[250:253], off offset:512
	s_not_b64 vcc, vcc
	v_cndmask_b32_dpp v200, v28, v24, vcc row_ror:8 row_mask:0xf bank_mask:0xf
	v_cndmask_b32_dpp v201, v29, v25, vcc row_ror:8 row_mask:0xf bank_mask:0xf
	v_cndmask_b32_dpp v202, v30, v26, vcc row_ror:8 row_mask:0xf bank_mask:0xf
	v_cndmask_b32_dpp v203, v31, v27, vcc row_ror:8 row_mask:0xf bank_mask:0xf
	global_store_dwordx4 v[234:235], v[200:203], off
	v_cndmask_b32_dpp v250, v20, v16, vcc row_ror:8 row_mask:0xf bank_mask:0xf
	v_cndmask_b32_dpp v251, v21, v17, vcc row_ror:8 row_mask:0xf bank_mask:0xf
	v_cndmask_b32_dpp v252, v22, v18, vcc row_ror:8 row_mask:0xf bank_mask:0xf
	v_cndmask_b32_dpp v253, v23, v19, vcc row_ror:8 row_mask:0xf bank_mask:0xf
	global_store_dwordx4 v[234:235], v[250:253], off offset:512
	s_not_b64 vcc, vcc
	v_mul_f32_e32 v196, v28, v28
	v_mul_f32_e32 v197, v29, v29
	v_fmac_f32_e32 v196, v30, v30
	v_fmac_f32_e32 v197, v31, v31
	v_fmac_f32_e32 v196, v24, v24
	v_fmac_f32_e32 v197, v25, v25
	v_fmac_f32_e32 v196, v26, v26
	v_fmac_f32_e32 v197, v27, v27
	v_fmac_f32_e32 v196, v20, v20
	v_fmac_f32_e32 v197, v21, v21
	v_fmac_f32_e32 v196, v22, v22
	v_fmac_f32_e32 v197, v23, v23
	v_fmac_f32_e32 v196, v16, v16
	v_fmac_f32_e32 v197, v17, v17
	v_fmac_f32_e32 v196, v18, v18
	v_fmac_f32_e32 v197, v19, v19
	v_add_f32_e32 v198, v196, v197
	ds_bpermute_b32 v199, v194, v198
	s_mov_b32 s34, 0xa0000
	v_lshl_add_u64 v[234:235], v[228:229], 0, s[34:35]
	v_pk_mul_f32 v[200:201], v[28:29], v[56:57]
	v_pk_mul_f32 v[202:203], v[30:31], v[58:59]
	v_pk_mul_f32 v[204:205], v[24:25], v[60:61]
	v_pk_mul_f32 v[236:237], v[26:27], v[62:63]
	v_cvt_pk_bf16_f32 v250, v200, v201
	v_cvt_pk_bf16_f32 v251, v202, v203
	v_cvt_pk_bf16_f32 v252, v204, v205
	v_cvt_pk_bf16_f32 v253, v236, v237
	global_store_dwordx4 v[234:235], v[250:253], off
	s_waitcnt lgkmcnt(0)
	v_add_f32_e32 v198, v198, v199
	ds_bpermute_b32 v199, v195, v198
	v_pk_mul_f32 v[200:201], v[20:21], v[64:65]
	v_pk_mul_f32 v[202:203], v[22:23], v[66:67]
	v_pk_mul_f32 v[204:205], v[16:17], v[68:69]
	v_pk_mul_f32 v[236:237], v[18:19], v[70:71]
	v_cvt_pk_bf16_f32 v250, v200, v201
	v_cvt_pk_bf16_f32 v251, v202, v203
	v_cvt_pk_bf16_f32 v252, v204, v205
	v_cvt_pk_bf16_f32 v253, v236, v237
	global_store_dwordx4 v[234:235], v[250:253], off offset:256
	s_mov_b32 s34, 0x5000
	v_lshl_add_u64 v[224:225], v[226:227], 0, s[34:35]
	s_waitcnt lgkmcnt(0)
	v_add_f32_e32 v198, v198, v199
	s_mov_b64 exec, s[4:5]
	global_store_dword v[224:225], v198, off
	s_mov_b64 exec, -1
	s_waitcnt vmcnt(21)
; __device__ __forceinline__ unsigned cvt_pk_bf16(float lo, float hi) { unsigned r; asm volatile("v_cvt_pk_bf16_f32 %0, %1, %2" : "=v"(r) : "v"(lo), "v"(hi)); return r; }
; #define PG8_BAR __builtin_amdgcn_s_barrier()
;     __device__ __forceinline__ void operator()(const f32x4 (&acc)[2][2][4][2], const Unit& u, int wr, int wc, int fr, int fq) const {
;     ...
;             for (int m = 0; m < 4; ++m) { const int row = row0 + ai * HALF + m * 16; const size_t off = (size_t)row * ldc + col0; float ss = 0.f;
; #pragma unroll
;                 for (int bj = 0; bj < 2; ++bj) {
;                     const f32x4 x0 = rb[m][bj][0] + acc[ai][bj][m][0], x1 = rb[m][bj][1] + acc[ai][bj][m][1];
;                     if (out) { *(f32x4*)(out + off + bj * HALF) = x0; *(f32x4*)(out + off + bj * HALF + 4) = x1; }
;                     ss += (x0[0] * x0[0] + x0[1] * x0[1]) + (x0[2] * x0[2] + x0[3] * x0[3]) + (x1[0] * x1[0] + x1[1] * x1[1]) + (x1[2] * x1[2] + x1[3] * x1[3]);
;                     const f32x4 y0 = x0 * gv[bj][0], y1 = x1 * gv[bj][1];
;                     u32x4 w; w.x = cvt_pk_bf16(y0[0], y0[1]); w.y = cvt_pk_bf16(y0[2], y0[3]); w.z = cvt_pk_bf16(y1[0], y1[1]); w.w = cvt_pk_bf16(y1[2], y1[3]);
;                     *(u32x4*)(XG + off + bj * HALF) = w; }
;                 ss += __shfl_xor(ss, 16); ss += __shfl_xor(ss, 32);
;                 if (fq == 0) SS[(size_t)row * 32 + u.pn * 4 + wc] = ss; }
; template <class Epi, class Sched, bool ALIGN_EPI = false, bool SP2 = false>
; __device__ __forceinline__ void gemm_phase(PG8_LAS unsigned char* lds, const Gemm g, const Sched& S, const Epi& E) {
;     ...
;         if constexpr (ALIGN_EPI) { if (wr == 0) PG8_BAR; }
;         if constexpr (!Epi::AFTER_DRAIN) { E(acc, cur, wr, wc, fr, fq); S.done(cur); }
;         if (!has_next) break;
; #pragma unroll
;         for (int a = 0; a < 2; ++a)
; #pragma unroll
;             for (int b = 0; b < 2; ++b)
; #pragma unroll
;                 for (int m = 0; m < 4; ++m)
; #pragma unroll
;                     for (int n = 0; n < 2; ++n) acc[a][b][m][n] = (f32x4){0.f, 0.f, 0.f, 0.f};
;         cur = nxt; cA = nA; cB = nB; ++ui;
;         if constexpr (ALIGN_EPI) { if (wr == 1) PG8_BAR; }
	v_pk_add_f32 v[12:13], v[12:13], v[162:163]
	v_pk_add_f32 v[14:15], v[14:15], v[164:165]
	v_pk_add_f32 v[8:9], v[8:9], v[166:167]
	v_pk_add_f32 v[10:11], v[10:11], v[168:169]
	v_pk_add_f32 v[4:5], v[4:5], v[170:171]
	v_pk_add_f32 v[6:7], v[6:7], v[172:173]
	v_pk_add_f32 v[0:1], v[0:1], v[174:175]
	v_pk_add_f32 v[2:3], v[2:3], v[176:177]
	s_mov_b32 s34, 0x160000
	v_lshl_add_u64 v[224:225], v[220:221], 0, s[34:35]
	v_lshl_add_u64 v[224:225], v[224:225], 0, s[40:41]
	v_lshl_add_u64 v[234:235], v[224:225], 0, v[222:223]
	v_lshl_add_u64 v[224:225], v[224:225], 0, v[218:219]
	v_cndmask_b32_dpp v200, v8, v12, vcc row_ror:8 row_mask:0xf bank_mask:0xf
	v_cndmask_b32_dpp v201, v9, v13, vcc row_ror:8 row_mask:0xf bank_mask:0xf
	v_cndmask_b32_dpp v202, v10, v14, vcc row_ror:8 row_mask:0xf bank_mask:0xf
	v_cndmask_b32_dpp v203, v11, v15, vcc row_ror:8 row_mask:0xf bank_mask:0xf
	global_store_dwordx4 v[224:225], v[200:203], off
	v_cndmask_b32_dpp v250, v0, v4, vcc row_ror:8 row_mask:0xf bank_mask:0xf
	v_cndmask_b32_dpp v251, v1, v5, vcc row_ror:8 row_mask:0xf bank_mask:0xf
	v_cndmask_b32_dpp v252, v2, v6, vcc row_ror:8 row_mask:0xf bank_mask:0xf
	v_cndmask_b32_dpp v253, v3, v7, vcc row_ror:8 row_mask:0xf bank_mask:0xf
	global_store_dwordx4 v[224:225], v[250:253], off offset:512
	s_not_b64 vcc, vcc
	v_cndmask_b32_dpp v200, v12, v8, vcc row_ror:8 row_mask:0xf bank_mask:0xf
	v_cndmask_b32_dpp v201, v13, v9, vcc row_ror:8 row_mask:0xf bank_mask:0xf
	v_cndmask_b32_dpp v202, v14, v10, vcc row_ror:8 row_mask:0xf bank_mask:0xf
	v_cndmask_b32_dpp v203, v15, v11, vcc row_ror:8 row_mask:0xf bank_mask:0xf
	global_store_dwordx4 v[234:235], v[200:203], off
	v_cndmask_b32_dpp v250, v4, v0, vcc row_ror:8 row_mask:0xf bank_mask:0xf
	v_cndmask_b32_dpp v251, v5, v1, vcc row_ror:8 row_mask:0xf bank_mask:0xf
	v_cndmask_b32_dpp v252, v6, v2, vcc row_ror:8 row_mask:0xf bank_mask:0xf
	v_cndmask_b32_dpp v253, v7, v3, vcc row_ror:8 row_mask:0xf bank_mask:0xf
	global_store_dwordx4 v[234:235], v[250:253], off offset:512
	s_not_b64 vcc, vcc
	v_mul_f32_e32 v196, v12, v12
	v_mul_f32_e32 v197, v13, v13
	v_fmac_f32_e32 v196, v14, v14
	v_fmac_f32_e32 v197, v15, v15
	v_fmac_f32_e32 v196, v8, v8
	v_fmac_f32_e32 v197, v9, v9
	v_fmac_f32_e32 v196, v10, v10
	v_fmac_f32_e32 v197, v11, v11
	v_fmac_f32_e32 v196, v4, v4
	v_fmac_f32_e32 v197, v5, v5
	v_fmac_f32_e32 v196, v6, v6
	v_fmac_f32_e32 v197, v7, v7
	v_fmac_f32_e32 v196, v0, v0
	v_fmac_f32_e32 v197, v1, v1
	v_fmac_f32_e32 v196, v2, v2
	v_fmac_f32_e32 v197, v3, v3
	v_add_f32_e32 v198, v196, v197
	ds_bpermute_b32 v199, v194, v198
	s_mov_b32 s34, 0xb0000
	v_lshl_add_u64 v[234:235], v[228:229], 0, s[34:35]
	v_pk_mul_f32 v[200:201], v[12:13], v[56:57]
	v_pk_mul_f32 v[202:203], v[14:15], v[58:59]
	v_pk_mul_f32 v[204:205], v[8:9], v[60:61]
	v_pk_mul_f32 v[236:237], v[10:11], v[62:63]
	v_cvt_pk_bf16_f32 v250, v200, v201
	v_cvt_pk_bf16_f32 v251, v202, v203
	v_cvt_pk_bf16_f32 v252, v204, v205
	v_cvt_pk_bf16_f32 v253, v236, v237
	global_store_dwordx4 v[234:235], v[250:253], off
	s_waitcnt lgkmcnt(0)
	v_add_f32_e32 v198, v198, v199
	ds_bpermute_b32 v199, v195, v198
	v_pk_mul_f32 v[200:201], v[4:5], v[64:65]
	v_pk_mul_f32 v[202:203], v[6:7], v[66:67]
	v_pk_mul_f32 v[204:205], v[0:1], v[68:69]
	v_pk_mul_f32 v[236:237], v[2:3], v[70:71]
	v_cvt_pk_bf16_f32 v250, v200, v201
	v_cvt_pk_bf16_f32 v251, v202, v203
	v_cvt_pk_bf16_f32 v252, v204, v205
	v_cvt_pk_bf16_f32 v253, v236, v237
	global_store_dwordx4 v[234:235], v[250:253], off offset:256
	s_mov_b32 s34, 0x5800
	v_lshl_add_u64 v[224:225], v[226:227], 0, s[34:35]
	s_waitcnt lgkmcnt(0)
	v_add_f32_e32 v198, v198, v199
	s_mov_b64 exec, s[4:5]
	global_store_dword v[224:225], v198, off
	s_mov_b64 exec, -1
	s_andn2_b64 vcc, exec, s[6:7]
	s_mov_b64 s[6:7], -1
	s_cbranch_vccnz .LBB0_1773
	s_andn2_b64 vcc, exec, s[12:13]
	s_cbranch_vccnz .LBB0_1772
	s_barrier
	s_branch .LBB0_1772
